# attention: per-item Q loads and epilogue gate loads (read once) marked nt, on top of the LN nt-store version
# baseline (speedup 1.0000x reference)
; #define LAS __attribute__((address_space(3)))
; DI size_t zrowU(int row0, int NT) { return ((size_t)((row0 >> 8) * NT) << 16) + (size_t)((((row0 >> 7) & 1) << 15) | (((row0 >> 5) & 1) << 14) | (((row0 >> 6) & 1) << 11)); }
; DI unsigned zlaneRC(int r5, int col) { return (unsigned)(((col >> 8) << 16) | ((r5 >> 4) << 13) | (((col >> 7) & 1) << 12) | (((col >> 5) & 3) << 9) | (((col >> 3) & 3) << 7) | ((r5 & 15) << 3) | (col & 7)); }
; DI void attnB_item(bf16_t* z, int hh, int qs, LAS bf16_t* vs, int lane) {
;     const int c = lane & 31, h = lane >> 5;
;     const bool metaq = qs < 0;
;     const int qrow = metaq ? SEQ + c : 32 * qs + c;
;     const int qpos = metaq ? (c < NMETA ? c : 0) : NMETA + 32 * qs + c;
;     const int trb = (4 * h + ((lane & 15) >> 2)) * PB + 16 * ((lane >> 4) & 1) + 4 * (lane & 3);
;     const int qrow0 = metaq ? SEQ : 32 * qs;
;     LAS bf16x8* qs_lds = (LAS bf16x8*)(vs + 32 * PB) + lane;
;     { const bf16_t* qp = z + zrowU(qrow0, 32) + zlaneRC(c, hh * 128 + 8 * h);
;       bf16x8 qf[8];
; #pragma unroll
;       for (int s = 0; s < 8; ++s) qf[s] = *(const bf16x8*)(qp + (((s >> 1) << 9) | ((s & 1) << 8)));
;       asm volatile("s_waitcnt lgkmcnt(0)" ::: "memory");
; #pragma unroll
;       for (int s = 0; s < 8; ++s) qs_lds[64 * s] = qf[s]; }
;     f32x16 acc[4];
; #pragma unroll
;     for (int dt = 0; dt < 4; ++dt)
; #pragma unroll
;         for (int i = 0; i < 16; ++i) acc[dt][i] = 0.f;
;     float later = 0.f;
;     int t = metaq ? -1 : qs;
;     const int tfirst = t;
;     const bf16_t* kbase = z + zlaneRC(c, 2048 + hh * 128 + 8 * h);
;     const bf16_t* vbase = z + zlaneRC(lane & 15, 4096 + hh * 128 + 8 * (lane >> 4));
;     bf16x8 kf[8]; u32x4 vv[8];
;     { const size_t ro = zrowU(t < 0 ? SEQ : 32 * t, 32);
; #pragma unroll
;       for (int s = 0; s < 8; ++s) kf[s] = *(const bf16x8*)(kbase + ro + (((s >> 1) << 9) | ((s & 1) << 8)));
; #pragma unroll
;       for (int i = 0; i < 8; ++i) vv[i] = *(const u32x4*)(vbase + ro + (((i >> 2) << 13) | ((i & 3) << 9))); }
.LBB0_149:
	s_lshr_b32 s5, s4, 3
	s_and_b32 s78, s5, 0x1fffffe0
	s_lshl_b32 s5, s4, 8
	s_lshl_b32 s7, s4, 9
	s_and_b32 s5, s5, 0x8000
	s_and_b32 s7, s7, 0x4000
	s_lshl_b32 s4, s4, 5
	s_or_b32 s5, s5, s7
	s_and_b32 s4, s4, 0x800
	s_or_b32 s7, s5, s4
	s_lshl_b64 s[4:5], s[78:79], 17
	s_add_u32 s4, s82, s4
	s_addc_u32 s5, s83, s5
	s_lshl_b32 s7, s7, 1
	s_add_u32 s46, s4, s7
	v_ashrrev_i32_e32 v180, 5, v2
	s_addc_u32 s47, s5, 0
	s_lshl_b32 s27, s23, 7
	v_lshl_add_u32 v0, v180, 3, s27
	v_lshlrev_b32_e32 v3, 8, v0
	v_lshlrev_b32_e32 v0, 5, v0
	v_and_b32_e32 v36, 0x1000, v0
	v_lshlrev_b32_e32 v0, 7, v180
	v_lshlrev_b32_e32 v4, 9, v178
	v_and_b32_e32 v37, 0x780, v0
	v_lshlrev_b32_e32 v0, 3, v178
	s_movk_i32 s4, 0x2078
	v_bitop3_b32 v181, v0, s4, v4 bitop3:0xc8
	v_and_b32_e32 v3, 0xffff0000, v3
	v_or_b32_e32 v0, v181, v37
	v_or3_b32 v0, v0, v36, v3
	v_lshl_add_u64 v[32:33], v[0:1], 1, s[46:47]
	global_load_dwordx4 v[4:7], v[32:33], off nt
	global_load_dwordx4 v[8:11], v[32:33], off offset:512 nt
	global_load_dwordx4 v[12:15], v[32:33], off offset:1024 nt
	global_load_dwordx4 v[16:19], v[32:33], off offset:1536 nt
	global_load_dwordx4 v[20:23], v[32:33], off offset:2048 nt
	global_load_dwordx4 v[24:27], v[32:33], off offset:2560 nt
	global_load_dwordx4 v[28:31], v[32:33], off offset:3072 nt
	s_nop 0
	global_load_dwordx4 v[32:35], v[32:33], off offset:3584 nt
	v_ashrrev_i32_e32 v41, 1, v2
	s_max_i32 s28, s6, -1
	v_bfe_u32 v0, v2, 2, 2
	v_lshlrev_b32_e32 v183, 2, v180
	v_and_b32_e32 v42, -8, v41
	s_add_i32 s4, s27, 0x1000
	s_lshl_b32 s6, s28, 5
	v_or_b32_e32 v44, v183, v0
	v_add_u32_e32 v0, s4, v42
	s_and_b64 s[4:5], exec, s[0:1]
	s_cselect_b32 s4, s6, 0x4000
	s_lshl_b32 s6, s4, 8
	s_lshl_b32 s7, s4, 9
	s_ashr_i32 s5, s4, 3
	s_lshl_b32 s8, s4, 5
	s_and_b32 s6, s6, 0x8000
	s_and_b32 s7, s7, 0x4000
	v_and_b32_e32 v38, 15, v2
	v_lshlrev_b32_e32 v45, 8, v0
	v_lshlrev_b32_e32 v0, 5, v0
	v_or_b32_e32 v3, v3, v36
	s_and_b32 s4, s5, 0xffffffe0
	s_and_b32 s8, s8, 0x800
	s_or_b32 s6, s6, s7
	v_lshlrev_b32_e32 v41, 4, v41
	v_lshlrev_b32_e32 v43, 3, v38
	v_and_b32_e32 v36, 0x1000, v0
	v_or3_b32 v0, v3, v37, v181
	s_ashr_i32 s5, s4, 31
	s_or_b32 s6, s6, s8
	v_and_b32_e32 v41, 0x780, v41
	v_and_or_b32 v43, v45, s12, v43
	v_add_u32_e32 v0, 0x80000, v0
	s_lshl_b64 s[4:5], s[4:5], 17
	s_lshl_b32 s6, s6, 1
	v_lshl_add_u64 v[158:159], v[0:1], 1, s[82:83]
	v_or3_b32 v0, v43, v36, v41
	s_or_b32 s4, s4, s6
	v_lshl_add_u32 v182, v2, 4, s25
	s_waitcnt lgkmcnt(0)
	v_lshl_add_u64 v[36:37], v[158:159], 0, s[4:5]
	v_lshl_add_u64 v[160:161], v[0:1], 1, s[82:83]
	global_load_dwordx4 v[114:117], v[36:37], off
	global_load_dwordx4 v[118:121], v[36:37], off offset:512
	global_load_dwordx4 v[122:125], v[36:37], off offset:1024
	global_load_dwordx4 v[126:129], v[36:37], off offset:1536
	v_and_b32_e32 v40, 16, v2
	v_lshlrev_b32_e32 v3, 3, v2
	v_lshlrev_b32_e32 v0, 1, v40
	v_and_b32_e32 v3, 24, v3
	v_lshlrev_b32_e32 v39, 2, v2
	v_add3_u32 v3, s25, v0, v3
	v_cmp_gt_u32_e64 s[36:37], 32, v2
	v_mov_b32_e32 v189, 0
	v_xor_b32_e32 v184, 0x80, v39
	v_or_b32_e32 v185, 1, v183
	v_or_b32_e32 v186, 2, v183
	v_or_b32_e32 v187, 3, v183
	v_add_u32_e32 v163, 10, v183
	v_add_u32_e32 v0, 8, v183
	v_add_u32_e32 v165, 11, v183
	v_add_u32_e32 v162, 9, v183
	v_add_u32_e32 v167, 18, v183
	v_add_u32_e32 v164, 16, v183
	v_add_u32_e32 v169, 19, v183
	v_add_u32_e32 v166, 17, v183
	v_add_u32_e32 v171, 26, v183
	s_waitcnt vmcnt(11)
	ds_write_b128 v182, v[4:7] offset:10240
	s_waitcnt vmcnt(10)
	ds_write_b128 v182, v[8:11] offset:11264
	s_waitcnt vmcnt(9)
	ds_write_b128 v182, v[12:15] offset:12288
	s_waitcnt vmcnt(8)
	ds_write_b128 v182, v[16:19] offset:13312
	s_waitcnt vmcnt(7)
	ds_write_b128 v182, v[20:23] offset:14336
	s_waitcnt vmcnt(6)
	ds_write_b128 v182, v[24:27] offset:15360
	s_waitcnt vmcnt(5)
	ds_write_b128 v182, v[28:31] offset:16384
	s_waitcnt vmcnt(4)
	ds_write_b128 v182, v[32:35] offset:17408
	v_lshl_add_u64 v[4:5], v[160:161], 0, s[4:5]
	global_load_dwordx4 v[130:133], v[36:37], off offset:2048
	global_load_dwordx4 v[134:137], v[36:37], off offset:2560
	global_load_dwordx4 v[138:141], v[36:37], off offset:3072
	global_load_dwordx4 v[142:145], v[36:37], off offset:3584
	global_load_dwordx4 v[82:85], v[4:5], off
	global_load_dwordx4 v[86:89], v[4:5], off offset:1024
	global_load_dwordx4 v[90:93], v[4:5], off offset:2048
	global_load_dwordx4 v[94:97], v[4:5], off offset:3072
	v_add_co_u32_e32 v4, vcc, s3, v4
	s_movk_i32 s4, 0x140
	s_nop 0
	v_addc_co_u32_e32 v5, vcc, 0, v5, vcc
	global_load_dwordx4 v[98:101], v[4:5], off
	global_load_dwordx4 v[102:105], v[4:5], off offset:1024
	global_load_dwordx4 v[106:109], v[4:5], off offset:2048
	global_load_dwordx4 v[110:113], v[4:5], off offset:3072
	v_mul_lo_u32 v2, v44, s4
	v_mul_u32_u24_e32 v4, 0x140, v38
	v_lshlrev_b32_e32 v5, 1, v42
	v_add_u32_e32 v168, 24, v183
	v_add_u32_e32 v173, 27, v183
	v_add_u32_e32 v170, 25, v183
	v_add3_u32 v188, s25, v4, v5
	v_add_u32_e32 v190, v3, v2
	s_mov_b32 s30, s28
	v_mov_b32_e32 v50, 0
	v_mov_b32_e32 v51, v189
	v_mov_b32_e32 v52, v189
	v_mov_b32_e32 v53, v189
	v_mov_b32_e32 v54, v189
	v_mov_b32_e32 v55, v189
	v_mov_b32_e32 v56, v189
	v_mov_b32_e32 v57, v189
	v_mov_b32_e32 v58, v189
	v_mov_b32_e32 v59, v189
	v_mov_b32_e32 v60, v189
	v_mov_b32_e32 v61, v189
	v_mov_b32_e32 v62, v189
	v_mov_b32_e32 v63, v189
	v_mov_b32_e32 v64, v189
	v_mov_b32_e32 v65, v189
	v_mov_b32_e32 v34, 0
	v_mov_b32_e32 v35, v189
	v_mov_b32_e32 v36, v189
	v_mov_b32_e32 v37, v189
	v_mov_b32_e32 v38, v189
	v_mov_b32_e32 v39, v189
	v_mov_b32_e32 v40, v189
	v_mov_b32_e32 v41, v189
	v_mov_b32_e32 v42, v189
	v_mov_b32_e32 v43, v189
	v_mov_b32_e32 v44, v189
	v_mov_b32_e32 v45, v189
	v_mov_b32_e32 v46, v189
	v_mov_b32_e32 v47, v189
	v_mov_b32_e32 v48, v189
	v_mov_b32_e32 v49, v189
	v_mov_b32_e32 v18, 0
	v_mov_b32_e32 v19, v189
	v_mov_b32_e32 v20, v189
	v_mov_b32_e32 v21, v189
	v_mov_b32_e32 v22, v189
	v_mov_b32_e32 v23, v189
	v_mov_b32_e32 v24, v189
	v_mov_b32_e32 v25, v189
	v_mov_b32_e32 v26, v189
	v_mov_b32_e32 v27, v189
	v_mov_b32_e32 v28, v189
	v_mov_b32_e32 v29, v189
	v_mov_b32_e32 v30, v189
	v_mov_b32_e32 v31, v189
	v_mov_b32_e32 v32, v189
	v_mov_b32_e32 v33, v189
	v_mov_b32_e32 v2, 0
	v_mov_b32_e32 v3, v189
	v_mov_b32_e32 v4, v189
	v_mov_b32_e32 v5, v189
	v_mov_b32_e32 v6, v189
	v_mov_b32_e32 v7, v189
	v_mov_b32_e32 v8, v189
	v_mov_b32_e32 v9, v189
	v_mov_b32_e32 v10, v189
	v_mov_b32_e32 v11, v189
	v_mov_b32_e32 v12, v189
	v_mov_b32_e32 v13, v189
	v_mov_b32_e32 v14, v189
	v_mov_b32_e32 v15, v189
	v_mov_b32_e32 v16, v189
	v_mov_b32_e32 v17, v189
	s_branch .LBB0_151

; #define LAS __attribute__((address_space(3)))
; DI size_t zrowU(int row0, int NT) { return ((size_t)((row0 >> 8) * NT) << 16) + (size_t)((((row0 >> 7) & 1) << 15) | (((row0 >> 5) & 1) << 14) | (((row0 >> 6) & 1) << 11)); }
; DI void attnA_item(bf16_t* z, const float* sinks, int hp, int qs, LAS bf16_t* vs, const LAS float* btab, int lane) {
;     const int c = lane & 31, h = lane >> 5, kvh = hp >> 2;
;     const bool metaq = qs < 0;
;     const int qrow = metaq ? SEQ + c : 32 * qs + c;
;     const int qpos = metaq ? (c < NMETA ? c : 0) : NMETA + 32 * qs + c;
;     const int trb = (4 * h + ((lane & 15) >> 2)) * PA + 16 * ((lane >> 4) & 1) + 4 * (lane & 3);
;     const int qrow0 = metaq ? SEQ : 32 * qs;
;     LAS bf16x8* qs_lds = (LAS bf16x8*)(vs + 32 * PA) + lane;
;     { bf16x8 qf[2][4];
; #pragma unroll
;       for (int u = 0; u < 2; ++u) { const bf16_t* qp = z + zrowU(qrow0, 18) + zlaneRC(c, (2 * hp + u) * 64 + 8 * h);
; #pragma unroll
;         for (int s = 0; s < 4; ++s) qf[u][s] = *(const bf16x8*)(qp + (((s >> 1) << 9) | ((s & 1) << 8))); }
;       asm volatile("s_waitcnt lgkmcnt(0)" ::: "memory");
; #pragma unroll
;       for (int u = 0; u < 2; ++u)
; #pragma unroll
;         for (int s = 0; s < 4; ++s) qs_lds[64 * (4 * u + s)] = qf[u][s]; }
;     f32x16 acc[2][2];
; #pragma unroll
;     for (int u = 0; u < 2; ++u)
; #pragma unroll
;         for (int dt = 0; dt < 2; ++dt)
; #pragma unroll
;             for (int i = 0; i < 16; ++i) acc[u][dt][i] = 0.f;
;     float m[2] = {sinks[2 * hp] * 1.4426950408889634f, sinks[2 * hp + 1] * 1.4426950408889634f}, l[2] = {1.0f, 1.0f};
;     const int tlo = metaq ? 0 : (qs - 4 > 0 ? qs - 4 : 0), thi = metaq ? -1 : qs;
;     const bf16_t* kbase = z + zlaneRC(c, 2048 + kvh * 64 + 8 * h);
;     const bf16_t* vbase = z + zlaneRC(lane & 15, 2304 + kvh * 64 + 8 * (lane >> 4));
;     bf16x8 kf[4]; u32x4 vv[4];
;     int t = -1;
;     { const size_t ro = zrowU(SEQ, 18);
; #pragma unroll
;       for (int s = 0; s < 4; ++s) kf[s] = *(const bf16x8*)(kbase + ro + (((s >> 1) << 9) | ((s & 1) << 8)));
; #pragma unroll
;       for (int i = 0; i < 4; ++i) vv[i] = *(const u32x4*)(vbase + ro + (((i >> 1) << 13) | ((i & 1) << 9))); }
.LBB0_196:
	s_lshr_b32 s0, s4, 8
	s_mul_i32 s78, s0, 18
	s_lshl_b32 s0, s4, 8
	s_lshl_b32 s1, s4, 9
	s_and_b32 s0, s0, 0x8000
	s_and_b32 s1, s1, 0x4000
	s_or_b32 s0, s0, s1
	s_lshl_b32 s1, s4, 5
	s_and_b32 s1, s1, 0x800
	s_or_b32 s4, s0, s1
	s_lshl_b64 s[0:1], s[78:79], 17
	s_add_u32 s0, s82, s0
	s_addc_u32 s1, s83, s1
	s_lshl_b32 s4, s4, 1
	v_ashrrev_i32_e32 v126, 5, v2
	s_add_u32 s0, s0, s4
	s_addc_u32 s1, s1, 0
	s_lshl_b32 s27, s22, 7
	v_lshlrev_b32_e32 v3, 3, v126
	v_add_u32_e32 v20, s27, v3
	v_lshlrev_b32_e32 v0, 9, v127
	v_lshlrev_b32_e32 v4, 3, v127
	s_movk_i32 s4, 0x2078
	v_bitop3_b32 v124, v4, s4, v0 bitop3:0xc8
	v_lshlrev_b32_e32 v4, 5, v20
	v_lshlrev_b32_e32 v0, 8, v20
	v_and_b32_e32 v4, 0x1000, v4
	v_lshlrev_b32_e32 v5, 7, v126
	s_movk_i32 s4, 0x780
	v_and_b32_e32 v0, 0xffff0000, v0
	v_and_or_b32 v4, v5, s4, v4
	v_or3_b32 v0, v4, v0, v124
	v_lshl_add_u64 v[16:17], v[0:1], 1, s[0:1]
	v_add_u32_e32 v0, 64, v20
	v_lshlrev_b32_e32 v20, 8, v0
	v_and_b32_e32 v20, 0xffff0000, v20
	v_lshlrev_b32_e32 v21, 5, v0
	v_lshlrev_b32_e32 v0, 4, v0
	s_lshl_b32 s4, s22, 1
	v_and_b32_e32 v0, 0x780, v0
	v_and_or_b32 v20, v21, s62, v20
	s_ashr_i32 s5, s4, 31
	v_or3_b32 v0, v20, v0, v124
	s_lshl_b64 s[4:5], s[4:5], 2
	v_lshl_add_u64 v[32:33], v[0:1], 1, s[0:1]
	s_add_u32 s4, s24, s4
	global_load_dwordx4 v[4:7], v[16:17], off nt
	global_load_dwordx4 v[8:11], v[16:17], off offset:512 nt
	global_load_dwordx4 v[12:15], v[16:17], off offset:1024 nt
	s_nop 0
	global_load_dwordx4 v[16:19], v[16:17], off offset:1536 nt
	s_nop 0
	global_load_dwordx4 v[20:23], v[32:33], off nt
	global_load_dwordx4 v[24:27], v[32:33], off offset:512 nt
	global_load_dwordx4 v[28:31], v[32:33], off offset:1024 nt
	s_nop 0
	global_load_dwordx4 v[32:35], v[32:33], off offset:1536 nt
	s_waitcnt lgkmcnt(0)
	s_addc_u32 s5, s25, s5
	global_load_dwordx2 v[36:37], v1, s[4:5]
	s_lshl_b32 s4, s22, 4
	s_andn2_b32 s4, s4, 63
	v_lshlrev_b32_e32 v125, 2, v126
	v_bfe_u32 v0, v2, 2, 2
	s_add_i32 s5, s4, 0x800
	v_or_b32_e32 v41, v125, v0
	v_add_u32_e32 v0, s5, v3
	v_lshlrev_b32_e32 v38, 5, v0
	v_lshlrev_b32_e32 v3, 8, v0
	v_and_b32_e32 v38, 0x1000, v38
	v_lshlrev_b32_e32 v0, 4, v0
	v_and_b32_e32 v0, 0x780, v0
	v_and_or_b32 v3, v3, s12, v38
	v_or3_b32 v0, v3, v0, v124
	v_lshl_add_u64 v[114:115], v[0:1], 1, s[82:83]
	v_ashrrev_i32_e32 v0, 1, v2
	s_addk_i32 s4, 0x900
	v_and_b32_e32 v3, -8, v0
	v_and_b32_e32 v40, 15, v2
	v_add_u32_e32 v0, s4, v3
	v_lshlrev_b32_e32 v38, 8, v0
	v_lshlrev_b32_e32 v39, 5, v0
	v_lshlrev_b32_e32 v0, 4, v0
	v_lshlrev_b32_e32 v44, 3, v40
	v_and_b32_e32 v39, 0x1000, v39
	v_and_b32_e32 v0, 0x780, v0
	v_and_or_b32 v38, v38, s12, v44
	s_mov_b32 s4, 0x9000000
	v_or3_b32 v0, v38, v39, v0
	v_add_co_u32_e32 v38, vcc, s4, v114
	v_lshl_add_u64 v[116:117], v[0:1], 1, s[82:83]
	s_nop 0
	v_addc_co_u32_e32 v39, vcc, 0, v115, vcc
	global_load_dwordx4 v[94:97], v[38:39], off
	global_load_dwordx4 v[90:93], v[38:39], off offset:512
	global_load_dwordx4 v[86:89], v[38:39], off offset:1024
	global_load_dwordx4 v[82:85], v[38:39], off offset:1536
	v_add_co_u32_e32 v38, vcc, s4, v116
	s_mov_b32 s4, 0x9004000
	s_nop 0
	v_addc_co_u32_e32 v39, vcc, 0, v117, vcc
	global_load_dwordx4 v[98:101], v[38:39], off
	global_load_dwordx4 v[102:105], v[38:39], off offset:1024
	v_add_co_u32_e32 v38, vcc, s4, v116
	v_sub_u32_e64 v0, s28, 4 clamp
	s_nop 0
	v_addc_co_u32_e32 v39, vcc, 0, v117, vcc
	global_load_dwordx4 v[106:109], v[38:39], off
	global_load_dwordx4 v[110:113], v[38:39], off offset:1024
	s_and_b64 s[4:5], s[68:69], exec
	v_lshlrev_b32_e32 v42, 2, v2
	v_and_b32_e32 v43, 16, v2
	v_lshl_add_u32 v129, v2, 4, s23
	v_readfirstlane_b32 s4, v0
	v_lshlrev_b32_e32 v2, 3, v2
	s_cselect_b32 s78, 0, s4
	v_lshlrev_b32_e32 v0, 1, v43
	v_and_b32_e32 v2, 24, v2
	s_movk_i32 s4, 0xc0
	s_waitcnt vmcnt(16)
	ds_write_b128 v129, v[4:7] offset:6144
	s_waitcnt vmcnt(15)
	ds_write_b128 v129, v[8:11] offset:7168
	s_waitcnt vmcnt(14)
	ds_write_b128 v129, v[12:15] offset:8192
	s_waitcnt vmcnt(13)
	ds_write_b128 v129, v[16:19] offset:9216
	s_waitcnt vmcnt(12)
	ds_write_b128 v129, v[20:23] offset:10240
	s_waitcnt vmcnt(11)
	ds_write_b128 v129, v[24:27] offset:11264
	s_waitcnt vmcnt(10)
	ds_write_b128 v129, v[28:31] offset:12288
	s_waitcnt vmcnt(9)
	ds_write_b128 v129, v[32:35] offset:13312
	v_add3_u32 v16, s23, v0, v2
	v_mul_lo_u32 v17, v41, s4
	s_mul_i32 s4, s22, 0x408
	v_mul_u32_u24_e32 v0, 0xc0, v40
	v_lshlrev_b32_e32 v2, 1, v3
	v_mov_b32_e32 v14, v1
	v_mov_b32_e32 v15, v1
	s_waitcnt vmcnt(8)
	v_pk_mul_f32 v[118:119], v[36:37], s[66:67] op_sel_hi:[1,0]
	v_xor_b32_e32 v145, 0x80, v42
	s_add_i32 s87, s4, 0
	v_add3_u32 v164, s23, v0, v2
	v_mov_b32_e32 v0, v1
	v_mov_b32_e32 v2, v1
	v_mov_b32_e32 v3, v1
	v_mov_b32_e32 v4, v1
	v_mov_b32_e32 v5, v1
	v_mov_b32_e32 v6, v1
	v_mov_b32_e32 v7, v1
	v_mov_b32_e32 v8, v1
	v_mov_b32_e32 v9, v1
	v_mov_b32_e32 v10, v1
	v_mov_b32_e32 v11, v1
	v_mov_b32_e32 v12, v1
	v_mov_b32_e32 v13, v1
	v_mov_b64_e32 v[64:65], v[14:15]
	v_mov_b64_e32 v[48:49], v[14:15]
	v_mov_b64_e32 v[32:33], v[14:15]
	s_add_i32 s87, s87, 0x1c000
	v_add_u32_e32 v165, v16, v17
	v_mov_b64_e32 v[62:63], v[12:13]
	v_mov_b64_e32 v[60:61], v[10:11]
	v_mov_b64_e32 v[58:59], v[8:9]
	v_mov_b64_e32 v[56:57], v[6:7]
	v_mov_b64_e32 v[54:55], v[4:5]
	v_mov_b64_e32 v[52:53], v[2:3]
	v_mov_b64_e32 v[50:51], v[0:1]
	v_mov_b64_e32 v[46:47], v[12:13]
	v_mov_b64_e32 v[44:45], v[10:11]
	v_mov_b64_e32 v[42:43], v[8:9]
	v_mov_b64_e32 v[40:41], v[6:7]
	v_mov_b64_e32 v[38:39], v[4:5]
	v_mov_b64_e32 v[36:37], v[2:3]
	v_mov_b64_e32 v[34:35], v[0:1]
	v_mov_b64_e32 v[30:31], v[12:13]
	v_mov_b64_e32 v[28:29], v[10:11]
	v_mov_b64_e32 v[26:27], v[8:9]
	v_mov_b64_e32 v[24:25], v[6:7]
	v_mov_b64_e32 v[22:23], v[4:5]
	v_mov_b64_e32 v[20:21], v[2:3]
	v_mov_b64_e32 v[18:19], v[0:1]
	v_mov_b64_e32 v[16:17], v[14:15]
	s_add_i32 s86, s28, -4
	v_or_b32_e32 v130, 1, v125
	v_or_b32_e32 v131, 2, v125
	v_or_b32_e32 v132, 3, v125
	v_add_u32_e32 v133, 8, v125
	v_add_u32_e32 v134, 9, v125
	v_add_u32_e32 v135, 10, v125
	v_add_u32_e32 v136, 11, v125
	v_add_u32_e32 v137, 16, v125
	v_add_u32_e32 v138, 17, v125
	v_add_u32_e32 v139, 18, v125
	v_add_u32_e32 v140, 19, v125
	v_add_u32_e32 v141, 24, v125
	v_add_u32_e32 v142, 25, v125
	v_add_u32_e32 v143, 26, v125
	v_add_u32_e32 v144, 27, v125
	v_add_u32_e32 v146, -3, v128
	v_add_u32_e32 v147, -8, v128
	v_add_u32_e32 v148, -9, v128
	v_add_u32_e32 v149, -10, v128
	v_add_u32_e32 v150, -11, v128
	v_add_u32_e32 v151, -16, v128
	v_subrev_u32_e32 v152, 17, v128
	v_subrev_u32_e32 v153, 18, v128
	v_subrev_u32_e32 v158, 19, v128
	v_subrev_u32_e32 v159, 24, v128
	v_subrev_u32_e32 v160, 25, v128
	v_subrev_u32_e32 v161, 26, v128
	v_subrev_u32_e32 v162, 27, v128
	v_lshl_add_u32 v163, v128, 2, s87
	s_mov_b32 s31, -1
	v_mov_b32_e32 v167, 1.0
	v_mov_b32_e32 v166, 1.0
	v_mov_b64_e32 v[14:15], v[12:13]
	v_mov_b64_e32 v[12:13], v[10:11]
	v_mov_b64_e32 v[10:11], v[8:9]
	v_mov_b64_e32 v[8:9], v[6:7]
	v_mov_b64_e32 v[6:7], v[4:5]
	v_mov_b64_e32 v[4:5], v[2:3]
	v_mov_b64_e32 v[2:3], v[0:1]
